# non-temporal hint also on the f32 weight loads of the in-projection slack conversions (read-once stream)
# speedup vs baseline: 1.0305x; 1.0065x over previous
; #define LAS __attribute__((address_space(3)))
; DI void ti_load(f32x4 (&v)[8], float (&g)[8], const TItem& ti) {
; #pragma unroll
;     for (int i = 0; i < 8; ++i) v[i] = *(const f32x4*)(ti.src + (size_t)(8 * i) * ti.N);
; #pragma unroll
;     for (int i = 0; i < 8; ++i) g[i] = ti.gp[8 * i];
; }
; template <int NS>
; DI void convert_flat(const CStack (&st)[NS], LAS float* scr, int gw, int NGW, int lane) {
;     const int total = cstack_total(st);
;     int it = gw;
;     if (it >= total) return;
;     TItem cur, nxt; f32x4 va[8], vb[8]; float ga[8], gb[8];
;     ti_decode(cur, it, st, lane); ti_load(va, ga, cur);
.LBB0_660:
	s_lshl_b32 s72, s20, 5
	v_lshl_add_u64 v[0:1], v[70:71], 0, s[72:73]
	v_lshl_add_u64 v[8:9], v[0:1], 0, s[72:73]
	global_load_dwordx4 v[0:3], v[0:1], off nt
	s_nop 0
	global_load_dwordx4 v[4:7], v[8:9], off nt
	v_lshl_add_u64 v[8:9], v[8:9], 0, s[72:73]
	v_lshl_add_u64 v[10:11], v[8:9], 0, s[72:73]
	global_load_dwordx4 v[12:15], v[8:9], off nt
	global_load_dwordx4 v[16:19], v[10:11], off nt
	v_lshl_add_u64 v[8:9], v[10:11], 0, s[72:73]
	v_lshl_add_u64 v[10:11], v[8:9], 0, s[72:73]
	v_lshl_add_u64 v[28:29], v[10:11], 0, s[72:73]
	global_load_dwordx4 v[20:23], v[8:9], off nt
	global_load_dwordx4 v[24:27], v[10:11], off nt
	s_nop 0
	global_load_dwordx4 v[8:11], v[70:71], off nt
	s_nop 0
	global_load_dwordx4 v[28:31], v[28:29], off nt
	s_nop 0
	global_load_dword v88, v[68:69], off
	global_load_dword v89, v[68:69], off offset:32
	global_load_dword v90, v[68:69], off offset:64
	global_load_dword v91, v[68:69], off offset:96
	global_load_dword v92, v[68:69], off offset:128
	global_load_dword v93, v[68:69], off offset:160
	global_load_dword v94, v[68:69], off offset:192
	global_load_dword v95, v[68:69], off offset:224
	v_lshl_add_u32 v32, v32, 2, s27
	v_mul_u32_u24_e32 v34, 0x90, v84
	v_lshl_add_u32 v35, v85, 2, s27
	v_mul_u32_u24_e32 v33, 0x90, v33
	v_lshl_add_u64 v[74:75], s[18:19], 0, v[152:153]
	v_add_u32_e32 v86, v32, v34
	v_add_u32_e32 v87, v35, v33
	s_mov_b32 s30, s28
	s_branch .LBB0_664

; #define LAS __attribute__((address_space(3)))
; DI unsigned pk2(float a, float b) { f32x2 v = {a, b}; hbf16x2 r = __builtin_convertvector(v, hbf16x2); return __builtin_bit_cast(unsigned, r); }
; DI void ti_load(f32x4 (&v)[8], float (&g)[8], const TItem& ti) {
; #pragma unroll
;     for (int i = 0; i < 8; ++i) v[i] = *(const f32x4*)(ti.src + (size_t)(8 * i) * ti.N);
; #pragma unroll
;     for (int i = 0; i < 8; ++i) g[i] = ti.gp[8 * i];
; }
; DI void ti_finish(const f32x4 (&v)[8], const float (&g)[8], const TItem& ti, LAS float* scr, int lane) {
;     const int q8 = lane & 7, kr = lane >> 3;
; #pragma unroll
;     for (int i = 0; i < 8; ++i) *(LAS f32x4*)(scr + (8 * i + kr) * 36 + 4 * q8) = v[i] * (ti.hasg ? g[i] : 1.0f);
;     asm volatile("s_waitcnt lgkmcnt(0)" ::: "memory");
;     const int n = lane & 31, kc = lane >> 5;
; #pragma unroll
;     for (int p2 = 0; p2 < 4; ++p2) { const int c = 2 * p2 + kc; const LAS float* s = scr + (8 * c) * 36 + n;
;         u32x4 o; o.x = pk2(s[0], s[36]); o.y = pk2(s[72], s[108]); o.z = pk2(s[144], s[180]); o.w = pk2(s[216], s[252]);
;         *(u32x4*)(ti.dst + 16 * p2) = o; }
;     asm volatile("s_waitcnt lgkmcnt(0)" ::: "memory");
; }
.LBB0_662:
	s_lshl_b64 s[22:23], s[22:23], 5
	global_load_dwordx4 v[8:11], v[0:1], off nt
	v_lshl_add_u64 v[0:1], v[0:1], 0, s[22:23]
	v_lshl_add_u64 v[12:13], v[0:1], 0, s[22:23]
	global_load_dwordx4 v[0:3], v[0:1], off nt
	s_nop 0
	global_load_dwordx4 v[4:7], v[12:13], off nt
	v_lshl_add_u64 v[12:13], v[12:13], 0, s[22:23]
	v_lshl_add_u64 v[20:21], v[12:13], 0, s[22:23]
	global_load_dwordx4 v[12:15], v[12:13], off nt
	s_nop 0
	global_load_dwordx4 v[16:19], v[20:21], off nt
	v_lshl_add_u64 v[20:21], v[20:21], 0, s[22:23]
	v_lshl_add_u64 v[28:29], v[20:21], 0, s[22:23]
	global_load_dwordx4 v[20:23], v[20:21], off nt
	s_nop 0
	global_load_dwordx4 v[24:27], v[28:29], off nt
	v_lshl_add_u64 v[28:29], v[28:29], 0, s[22:23]
	global_load_dwordx4 v[28:31], v[28:29], off nt
	s_nop 0
	global_load_dword v88, v[68:69], off
	global_load_dword v89, v[68:69], off offset:32
	global_load_dword v90, v[68:69], off offset:64
	global_load_dword v91, v[68:69], off offset:96
	global_load_dword v92, v[68:69], off offset:128
	global_load_dword v93, v[68:69], off offset:160
	global_load_dword v94, v[68:69], off offset:192
	global_load_dword v95, v[68:69], off offset:224
	s_cmp_eq_u32 s31, 0
	s_cselect_b64 s[22:23], -1, 0
	s_waitcnt vmcnt(27)
	v_cndmask_b32_e64 v110, v103, 1.0, s[22:23]
	v_pk_mul_f32 v[58:59], v[58:59], v[110:111] op_sel_hi:[1,0]
	v_pk_mul_f32 v[56:57], v[56:57], v[110:111] op_sel_hi:[1,0]
	ds_write_b128 v86, v[56:59]
	s_waitcnt vmcnt(26)
	v_cndmask_b32_e64 v56, v102, 1.0, s[22:23]
	v_pk_mul_f32 v[58:59], v[62:63], v[56:57] op_sel_hi:[1,0]
	v_pk_mul_f32 v[56:57], v[60:61], v[56:57] op_sel_hi:[1,0]
	ds_write_b128 v86, v[56:59] offset:1152
	s_waitcnt vmcnt(25)
	v_cndmask_b32_e64 v56, v101, 1.0, s[22:23]
	v_pk_mul_f32 v[54:55], v[54:55], v[56:57] op_sel_hi:[1,0]
	v_pk_mul_f32 v[52:53], v[52:53], v[56:57] op_sel_hi:[1,0]
	ds_write_b128 v86, v[52:55] offset:2304
	s_waitcnt vmcnt(24)
	v_cndmask_b32_e64 v52, v100, 1.0, s[22:23]
	v_pk_mul_f32 v[50:51], v[50:51], v[52:53] op_sel_hi:[1,0]
	v_pk_mul_f32 v[48:49], v[48:49], v[52:53] op_sel_hi:[1,0]
	ds_write_b128 v86, v[48:51] offset:3456
	s_waitcnt vmcnt(23)
	v_cndmask_b32_e64 v48, v99, 1.0, s[22:23]
	v_pk_mul_f32 v[46:47], v[46:47], v[48:49] op_sel_hi:[1,0]
	v_pk_mul_f32 v[44:45], v[44:45], v[48:49] op_sel_hi:[1,0]
	ds_write_b128 v86, v[44:47] offset:4608
	s_waitcnt vmcnt(22)
	v_cndmask_b32_e64 v44, v98, 1.0, s[22:23]
	v_pk_mul_f32 v[42:43], v[42:43], v[44:45] op_sel_hi:[1,0]
	v_pk_mul_f32 v[40:41], v[40:41], v[44:45] op_sel_hi:[1,0]
	ds_write_b128 v86, v[40:43] offset:5760
	s_waitcnt vmcnt(21)
	v_cndmask_b32_e64 v40, v97, 1.0, s[22:23]
	v_pk_mul_f32 v[38:39], v[38:39], v[40:41] op_sel_hi:[1,0]
	v_pk_mul_f32 v[36:37], v[36:37], v[40:41] op_sel_hi:[1,0]
	ds_write_b128 v86, v[36:39] offset:6912
	s_waitcnt vmcnt(20)
	v_cndmask_b32_e64 v36, v96, 1.0, s[22:23]
	v_pk_mul_f32 v[34:35], v[34:35], v[36:37] op_sel_hi:[1,0]
	v_pk_mul_f32 v[32:33], v[32:33], v[36:37] op_sel_hi:[1,0]
	ds_write_b128 v86, v[32:35] offset:8064
	s_waitcnt lgkmcnt(0)
	ds_read2_b32 v[32:33], v87 offset1:36
	ds_read2_b32 v[34:35], v87 offset0:72 offset1:108
	ds_read2_b32 v[36:37], v87 offset0:144 offset1:180
	ds_read2_b32 v[38:39], v87 offset0:216 offset1:252
	s_and_b64 s[22:23], s[20:21], exec
	s_waitcnt lgkmcnt(3)
	v_cvt_pk_bf16_f32 v32, v32, v33
	s_waitcnt lgkmcnt(2)
	v_cvt_pk_bf16_f32 v33, v34, v35
	s_waitcnt lgkmcnt(1)
	v_cvt_pk_bf16_f32 v34, v36, v37
	s_waitcnt lgkmcnt(0)
	v_cvt_pk_bf16_f32 v35, v38, v39
	ds_read2_b32 v[36:37], v104 offset0:64 offset1:100
	ds_read2_b32 v[38:39], v104 offset0:136 offset1:172
	ds_read2_b32 v[40:41], v104 offset0:208 offset1:244
	ds_read2_b32 v[42:43], v105 offset0:24 offset1:60
	global_store_dwordx4 v[80:81], v[32:35], off
	s_cselect_b32 s30, s19, s30
	s_waitcnt lgkmcnt(3)
	v_cvt_pk_bf16_f32 v32, v36, v37
	s_waitcnt lgkmcnt(2)
	v_cvt_pk_bf16_f32 v33, v38, v39
	s_waitcnt lgkmcnt(1)
	v_cvt_pk_bf16_f32 v34, v40, v41
	s_waitcnt lgkmcnt(0)
	v_cvt_pk_bf16_f32 v35, v42, v43
	ds_read2_b32 v[36:37], v106 offset0:128 offset1:164
	ds_read2_b32 v[38:39], v106 offset0:200 offset1:236
	ds_read2_b32 v[40:41], v107 offset0:16 offset1:52
	ds_read2_b32 v[42:43], v107 offset0:88 offset1:124
	global_store_dwordx4 v[80:81], v[32:35], off offset:32
	s_waitcnt lgkmcnt(3)
	s_nop 0
	v_cvt_pk_bf16_f32 v32, v36, v37
	s_waitcnt lgkmcnt(2)
	v_cvt_pk_bf16_f32 v33, v38, v39
	s_waitcnt lgkmcnt(1)
	v_cvt_pk_bf16_f32 v34, v40, v41
	s_waitcnt lgkmcnt(0)
	v_cvt_pk_bf16_f32 v35, v42, v43
	ds_read2_b32 v[36:37], v108 offset0:192 offset1:228
	ds_read2_b32 v[38:39], v109 offset0:8 offset1:44
	ds_read2_b32 v[40:41], v109 offset0:80 offset1:116
	ds_read2_b32 v[42:43], v109 offset0:152 offset1:188
	global_store_dwordx4 v[80:81], v[32:35], off offset:64
	s_waitcnt lgkmcnt(3)
	s_nop 0
	v_cvt_pk_bf16_f32 v32, v36, v37
	s_waitcnt lgkmcnt(2)
	v_cvt_pk_bf16_f32 v33, v38, v39
	s_waitcnt lgkmcnt(1)
	v_cvt_pk_bf16_f32 v34, v40, v41
	s_waitcnt lgkmcnt(0)
	v_cvt_pk_bf16_f32 v35, v42, v43
	global_store_dwordx4 v[80:81], v[32:35], off offset:96
	s_waitcnt lgkmcnt(0)

; #define LAS __attribute__((address_space(3)))
; DI unsigned pk2(float a, float b) { f32x2 v = {a, b}; hbf16x2 r = __builtin_convertvector(v, hbf16x2); return __builtin_bit_cast(unsigned, r); }
; template <int NS>
; DI void ti_decode(TItem& ti, int it, const CStack (&st)[NS], int lane) {
;     int base = 0;
; #pragma unroll
;     for (int j = 0; j < NS; ++j) {
;         const int nblk = st[j].N / 32, per = (st[j].K / 64) * nblk, tot = st[j].L * per;
;         if (it >= base && (it < base + tot || j == NS - 1)) {
;             const int K = st[j].K, N = st[j].N, r0 = it - base, l = r0 / per, rem = r0 - l * per, kb = rem / nblk, nb = rem - kb * nblk, k0 = 64 * kb;
;             ti.src = st[j].W + (size_t)l * K * N + (size_t)(k0 + (lane >> 3)) * N + (st[j].perm ? even_src32(nb) : 32 * nb) + 4 * (lane & 7);
;             ti.dst = st[j].WT + (size_t)l * K * N + (size_t)(32 * nb + (lane & 31)) * K + k0 + 8 * (lane >> 5);
;             ti.hasg = st[j].gk != nullptr; ti.gp = ti.hasg ? st[j].gk + (size_t)l * st[j].gstride + k0 + (lane >> 3) : ti.src;
;             ti.N = N;
;         }
;         base += tot;
;     }
; }
; #pragma unroll
;     for (int j = 0; j < NS; ++j) t += st[j].L * (st[j].K / 64) * (st[j].N / 32);
;     return t; }
; DI void ti_load(f32x4 (&v)[8], float (&g)[8], const TItem& ti) {
; #pragma unroll
;     for (int i = 0; i < 8; ++i) v[i] = *(const f32x4*)(ti.src + (size_t)(8 * i) * ti.N);
; #pragma unroll
;     for (int i = 0; i < 8; ++i) g[i] = ti.gp[8 * i];
; }
; DI void ti_finish(const f32x4 (&v)[8], const float (&g)[8], const TItem& ti, LAS float* scr, int lane) {
;     const int q8 = lane & 7, kr = lane >> 3;
; #pragma unroll
;     for (int i = 0; i < 8; ++i) *(LAS f32x4*)(scr + (8 * i + kr) * 36 + 4 * q8) = v[i] * (ti.hasg ? g[i] : 1.0f);
;     asm volatile("s_waitcnt lgkmcnt(0)" ::: "memory");
;     const int n = lane & 31, kc = lane >> 5;
; #pragma unroll
;     for (int p2 = 0; p2 < 4; ++p2) { const int c = 2 * p2 + kc; const LAS float* s = scr + (8 * c) * 36 + n;
;         u32x4 o; o.x = pk2(s[0], s[36]); o.y = pk2(s[72], s[108]); o.z = pk2(s[144], s[180]); o.w = pk2(s[216], s[252]);
;         *(u32x4*)(ti.dst + 16 * p2) = o; }
;     asm volatile("s_waitcnt lgkmcnt(0)" ::: "memory");
; }
.LBB0_673:
	s_lshl_b64 s[20:21], s[20:21], 5
	v_lshl_add_u64 v[32:33], v[78:79], 0, s[20:21]
	global_load_dwordx4 v[56:59], v[78:79], off nt
	global_load_dwordx4 v[60:63], v[32:33], off nt
	v_lshl_add_u64 v[32:33], v[32:33], 0, s[20:21]
	global_load_dwordx4 v[52:55], v[32:33], off nt
	v_lshl_add_u64 v[32:33], v[32:33], 0, s[20:21]
	global_load_dwordx4 v[48:51], v[32:33], off nt
	v_lshl_add_u64 v[32:33], v[32:33], 0, s[20:21]
	global_load_dwordx4 v[44:47], v[32:33], off nt
	v_lshl_add_u64 v[32:33], v[32:33], 0, s[20:21]
	global_load_dwordx4 v[40:43], v[32:33], off nt
	v_lshl_add_u64 v[32:33], v[32:33], 0, s[20:21]
	global_load_dwordx4 v[36:39], v[32:33], off nt
	v_lshl_add_u64 v[32:33], v[32:33], 0, s[20:21]
	global_load_dwordx4 v[32:35], v[32:33], off nt
	s_nop 0
	global_load_dword v103, v[76:77], off
	global_load_dword v102, v[76:77], off offset:32
	global_load_dword v101, v[76:77], off offset:64
	global_load_dword v100, v[76:77], off offset:96
	global_load_dword v99, v[76:77], off offset:128
	global_load_dword v98, v[76:77], off offset:160
	global_load_dword v97, v[76:77], off offset:192
	global_load_dword v96, v[76:77], off offset:224
	s_cmp_eq_u32 s29, 0
	s_cselect_b64 s[20:21], -1, 0
	s_waitcnt vmcnt(23)
	v_cndmask_b32_e64 v104, v88, 1.0, s[20:21]
	v_pk_mul_f32 v[106:107], v[10:11], v[104:105] op_sel_hi:[1,0]
	v_pk_mul_f32 v[104:105], v[8:9], v[104:105] op_sel_hi:[1,0]
	ds_write_b128 v86, v[104:107]
	s_waitcnt vmcnt(22)
	v_cndmask_b32_e64 v104, v89, 1.0, s[20:21]
	v_pk_mul_f32 v[106:107], v[2:3], v[104:105] op_sel_hi:[1,0]
	v_pk_mul_f32 v[104:105], v[0:1], v[104:105] op_sel_hi:[1,0]
	ds_write_b128 v86, v[104:107] offset:1152
	s_waitcnt vmcnt(21)
	v_cndmask_b32_e64 v104, v90, 1.0, s[20:21]
	v_pk_mul_f32 v[106:107], v[6:7], v[104:105] op_sel_hi:[1,0]
	v_pk_mul_f32 v[104:105], v[4:5], v[104:105] op_sel_hi:[1,0]
	ds_write_b128 v86, v[104:107] offset:2304
	s_waitcnt vmcnt(20)
	v_cndmask_b32_e64 v104, v91, 1.0, s[20:21]
	v_pk_mul_f32 v[106:107], v[14:15], v[104:105] op_sel_hi:[1,0]
	v_pk_mul_f32 v[104:105], v[12:13], v[104:105] op_sel_hi:[1,0]
	ds_write_b128 v86, v[104:107] offset:3456
	s_waitcnt vmcnt(19)
	v_cndmask_b32_e64 v104, v92, 1.0, s[20:21]
	v_pk_mul_f32 v[106:107], v[18:19], v[104:105] op_sel_hi:[1,0]
	v_pk_mul_f32 v[104:105], v[16:17], v[104:105] op_sel_hi:[1,0]
	ds_write_b128 v86, v[104:107] offset:4608
	s_waitcnt vmcnt(18)
	v_cndmask_b32_e64 v104, v93, 1.0, s[20:21]
	v_pk_mul_f32 v[106:107], v[22:23], v[104:105] op_sel_hi:[1,0]
	v_pk_mul_f32 v[104:105], v[20:21], v[104:105] op_sel_hi:[1,0]
	ds_write_b128 v86, v[104:107] offset:5760
	s_waitcnt vmcnt(17)
	v_cndmask_b32_e64 v104, v94, 1.0, s[20:21]
	v_pk_mul_f32 v[106:107], v[26:27], v[104:105] op_sel_hi:[1,0]
	v_pk_mul_f32 v[104:105], v[24:25], v[104:105] op_sel_hi:[1,0]
	ds_write_b128 v86, v[104:107] offset:6912
	s_waitcnt vmcnt(16)
	v_cndmask_b32_e64 v104, v95, 1.0, s[20:21]
	v_pk_mul_f32 v[106:107], v[30:31], v[104:105] op_sel_hi:[1,0]
	v_pk_mul_f32 v[104:105], v[28:29], v[104:105] op_sel_hi:[1,0]
	ds_write_b128 v86, v[104:107] offset:8064
	s_waitcnt lgkmcnt(0)
	ds_read2_b32 v[104:105], v87 offset1:36
	ds_read2_b32 v[106:107], v87 offset0:72 offset1:108
	ds_read2_b32 v[108:109], v87 offset0:216 offset1:252
	s_mov_b64 s[20:21], 0
	s_andn2_b64 vcc, exec, s[22:23]
	s_waitcnt lgkmcnt(2)
	v_cvt_pk_bf16_f32 v104, v104, v105
	s_waitcnt lgkmcnt(1)
	v_cvt_pk_bf16_f32 v105, v106, v107
	ds_read2_b32 v[106:107], v87 offset0:144 offset1:180
	s_waitcnt lgkmcnt(0)
	v_cvt_pk_bf16_f32 v106, v106, v107
	v_cvt_pk_bf16_f32 v107, v108, v109
	global_store_dwordx4 v[72:73], v[104:107], off
	s_nop 1
	v_add_u32_e32 v104, 0x800, v87
	ds_read2_b32 v[106:107], v104 offset0:64 offset1:100
	ds_read2_b32 v[108:109], v104 offset0:136 offset1:172
	v_add_u32_e32 v105, 0xc00, v87
	ds_read2_b32 v[110:111], v105 offset0:24 offset1:60
	s_waitcnt lgkmcnt(2)
	v_cvt_pk_bf16_f32 v106, v106, v107
	s_waitcnt lgkmcnt(1)
	v_cvt_pk_bf16_f32 v107, v108, v109
	ds_read2_b32 v[108:109], v104 offset0:208 offset1:244
	s_waitcnt lgkmcnt(0)
	v_cvt_pk_bf16_f32 v108, v108, v109
	v_cvt_pk_bf16_f32 v109, v110, v111
	global_store_dwordx4 v[72:73], v[106:109], off offset:32
	s_nop 1
	v_add_u32_e32 v106, 0x1000, v87
	ds_read2_b32 v[108:109], v106 offset0:128 offset1:164
	ds_read2_b32 v[110:111], v106 offset0:200 offset1:236
	v_add_u32_e32 v107, 0x1400, v87
	ds_read2_b32 v[112:113], v107 offset0:88 offset1:124
	s_waitcnt lgkmcnt(2)
	v_cvt_pk_bf16_f32 v108, v108, v109
	s_waitcnt lgkmcnt(1)
	v_cvt_pk_bf16_f32 v109, v110, v111
	ds_read2_b32 v[110:111], v107 offset0:16 offset1:52
	s_waitcnt lgkmcnt(0)
	v_cvt_pk_bf16_f32 v110, v110, v111
	v_cvt_pk_bf16_f32 v111, v112, v113
	global_store_dwordx4 v[72:73], v[108:111], off offset:64
	s_nop 1
	v_add_u32_e32 v108, 0x1800, v87
	v_add_u32_e32 v109, 0x1c00, v87
	ds_read2_b32 v[110:111], v108 offset0:192 offset1:228
	ds_read2_b32 v[112:113], v109 offset0:8 offset1:44
	ds_read2_b32 v[114:115], v109 offset0:152 offset1:188
	s_waitcnt lgkmcnt(2)
	v_cvt_pk_bf16_f32 v110, v110, v111
	s_waitcnt lgkmcnt(1)
	v_cvt_pk_bf16_f32 v111, v112, v113
	ds_read2_b32 v[112:113], v109 offset0:80 offset1:116
	s_waitcnt lgkmcnt(0)
	v_cvt_pk_bf16_f32 v112, v112, v113
	v_cvt_pk_bf16_f32 v113, v114, v115
	global_store_dwordx4 v[72:73], v[110:113], off offset:96
	s_waitcnt lgkmcnt(0)
	s_cbranch_vccnz .LBB0_663
	s_add_i32 s19, s17, s33
	s_cmpk_lt_i32 s19, 0x3000
	s_cselect_b64 s[20:21], -1, 0
	s_and_b64 s[22:23], s[20:21], exec
	s_cselect_b32 s17, s19, s17
	s_cmpk_gt_u32 s17, 0x1fff
	s_cbranch_scc1 .LBB0_678
	s_lshr_b32 s16, s17, 2
	s_and_b32 s16, s16, 0x7c0
	v_or_b32_e32 v0, s16, v84
	s_lshl_b32 s22, s17, 5
	v_lshlrev_b32_e32 v152, 15, v0
	s_and_b32 s22, s22, 0x1fe0
	v_lshl_add_u64 v[0:1], s[0:1], 0, v[152:153]
	s_lshl_b32 s72, s22, 2
	v_lshl_add_u64 v[0:1], v[0:1], 0, s[72:73]
	v_mov_b32_e32 v65, v153
	v_lshl_add_u64 v[70:71], v[0:1], 0, v[64:65]
	v_or_b32_e32 v0, s22, v85
	v_lshlrev_b32_e32 v152, 12, v0
	v_lshl_add_u64 v[0:1], s[2:3], 0, v[152:153]
	s_lshl_b32 s72, s16, 1
	v_lshl_add_u64 v[0:1], v[0:1], 0, s[72:73]
	v_mov_b32_e32 v67, v153
	s_lshl_b32 s72, s16, 2
	s_mov_b32 s29, 1
	v_lshl_add_u64 v[72:73], v[0:1], 0, v[66:67]
	v_lshl_add_u64 v[68:69], v[74:75], 0, s[72:73]
	s_movk_i32 s16, 0x2000
	s_and_b32 s22, s17, 0xfffff800
	s_cmpk_lg_i32 s22, 0x2000
	s_cbranch_scc0 .LBB0_679

; #define LAS __attribute__((address_space(3)))
; DI void ti_load(f32x4 (&v)[8], float (&g)[8], const TItem& ti) {
; #pragma unroll
;     for (int i = 0; i < 8; ++i) v[i] = *(const f32x4*)(ti.src + (size_t)(8 * i) * ti.N);
; #pragma unroll
;     for (int i = 0; i < 8; ++i) g[i] = ti.gp[8 * i];
; }
; template <int NS>
; DI void convert_flat(const CStack (&st)[NS], LAS float* scr, int gw, int NGW, int lane) {
;     const int total = cstack_total(st);
;     int it = gw;
;     if (it >= total) return;
;     TItem cur, nxt; f32x4 va[8], vb[8]; float ga[8], gb[8];
;     ti_decode(cur, it, st, lane); ti_load(va, ga, cur);
.LBB0_689:
	s_lshl_b32 s72, s6, 5
	v_lshl_add_u64 v[0:1], v[76:77], 0, s[72:73]
	v_lshl_add_u64 v[2:3], v[0:1], 0, s[72:73]
	global_load_dwordx4 v[24:27], v[0:1], off nt
	global_load_dwordx4 v[20:23], v[2:3], off nt
	v_lshl_add_u64 v[0:1], v[2:3], 0, s[72:73]
	v_lshl_add_u64 v[2:3], v[0:1], 0, s[72:73]
	global_load_dwordx4 v[16:19], v[0:1], off nt
	global_load_dwordx4 v[12:15], v[2:3], off nt
	v_lshl_add_u64 v[0:1], v[2:3], 0, s[72:73]
	v_lshl_add_u64 v[8:9], v[0:1], 0, s[72:73]
	global_load_dwordx4 v[4:7], v[0:1], off nt
	s_nop 0
	global_load_dwordx4 v[0:3], v[8:9], off nt
	v_lshl_add_u64 v[8:9], v[8:9], 0, s[72:73]
	global_load_dwordx4 v[28:31], v[76:77], off nt
	s_nop 0
	global_load_dwordx4 v[8:11], v[8:9], off nt
	s_nop 0
	global_load_dword v99, v[80:81], off
	global_load_dword v98, v[80:81], off offset:32
	global_load_dword v97, v[80:81], off offset:64
	global_load_dword v96, v[80:81], off offset:96
	global_load_dword v95, v[80:81], off offset:128
	global_load_dword v94, v[80:81], off offset:160
	global_load_dword v93, v[80:81], off offset:192
	global_load_dword v92, v[80:81], off offset:224
	v_lshl_add_u32 v32, v32, 2, s27
	v_mul_u32_u24_e32 v34, 0x90, v88
	v_lshl_add_u32 v35, v89, 2, s27
	v_mul_u32_u24_e32 v33, 0x90, v33
	s_add_i32 s18, s83, s26
	v_add_u32_e32 v90, v32, v34
	v_add_u32_e32 v91, v35, v33
	s_branch .LBB0_693

; #define LAS __attribute__((address_space(3)))
; DI unsigned pk2(float a, float b) { f32x2 v = {a, b}; hbf16x2 r = __builtin_convertvector(v, hbf16x2); return __builtin_bit_cast(unsigned, r); }
; DI void ti_load(f32x4 (&v)[8], float (&g)[8], const TItem& ti) {
; #pragma unroll
;     for (int i = 0; i < 8; ++i) v[i] = *(const f32x4*)(ti.src + (size_t)(8 * i) * ti.N);
; #pragma unroll
;     for (int i = 0; i < 8; ++i) g[i] = ti.gp[8 * i];
; }
; DI void ti_finish(const f32x4 (&v)[8], const float (&g)[8], const TItem& ti, LAS float* scr, int lane) {
;     const int q8 = lane & 7, kr = lane >> 3;
; #pragma unroll
;     for (int i = 0; i < 8; ++i) *(LAS f32x4*)(scr + (8 * i + kr) * 36 + 4 * q8) = v[i] * (ti.hasg ? g[i] : 1.0f);
;     asm volatile("s_waitcnt lgkmcnt(0)" ::: "memory");
;     const int n = lane & 31, kc = lane >> 5;
; #pragma unroll
;     for (int p2 = 0; p2 < 4; ++p2) { const int c = 2 * p2 + kc; const LAS float* s = scr + (8 * c) * 36 + n;
;         u32x4 o; o.x = pk2(s[0], s[36]); o.y = pk2(s[72], s[108]); o.z = pk2(s[144], s[180]); o.w = pk2(s[216], s[252]);
;         *(u32x4*)(ti.dst + 16 * p2) = o; }
;     asm volatile("s_waitcnt lgkmcnt(0)" ::: "memory");
; }
.LBB0_691:
	s_lshl_b64 s[12:13], s[12:13], 5
	v_lshl_add_u64 v[0:1], v[82:83], 0, s[12:13]
	v_lshl_add_u64 v[2:3], v[0:1], 0, s[12:13]
	global_load_dwordx4 v[24:27], v[0:1], off nt
	global_load_dwordx4 v[20:23], v[2:3], off nt
	v_lshl_add_u64 v[0:1], v[2:3], 0, s[12:13]
	v_lshl_add_u64 v[2:3], v[0:1], 0, s[12:13]
	global_load_dwordx4 v[16:19], v[0:1], off nt
	global_load_dwordx4 v[12:15], v[2:3], off nt
	v_lshl_add_u64 v[0:1], v[2:3], 0, s[12:13]
	v_lshl_add_u64 v[8:9], v[0:1], 0, s[12:13]
	global_load_dwordx4 v[4:7], v[0:1], off nt
	s_nop 0
	global_load_dwordx4 v[0:3], v[8:9], off nt
	v_lshl_add_u64 v[8:9], v[8:9], 0, s[12:13]
	global_load_dwordx4 v[28:31], v[82:83], off nt
	s_nop 0
	global_load_dwordx4 v[8:11], v[8:9], off nt
	s_nop 0
	global_load_dword v99, v[86:87], off
	global_load_dword v98, v[86:87], off offset:32
	global_load_dword v97, v[86:87], off offset:64
	global_load_dword v96, v[86:87], off offset:96
	global_load_dword v95, v[86:87], off offset:128
	global_load_dword v94, v[86:87], off offset:160
	global_load_dword v93, v[86:87], off offset:192
	global_load_dword v92, v[86:87], off offset:224
	s_cmp_eq_u32 s7, 0
	s_cselect_b64 s[12:13], -1, 0
	s_waitcnt vmcnt(27)
	v_cndmask_b32_e64 v76, v107, 1.0, s[12:13]
	v_pk_mul_f32 v[62:63], v[62:63], v[76:77] op_sel_hi:[1,0]
	v_pk_mul_f32 v[60:61], v[60:61], v[76:77] op_sel_hi:[1,0]
	ds_write_b128 v90, v[60:63]
	s_waitcnt vmcnt(26)
	v_cndmask_b32_e64 v60, v106, 1.0, s[12:13]
	v_pk_mul_f32 v[58:59], v[58:59], v[60:61] op_sel_hi:[1,0]
	v_pk_mul_f32 v[56:57], v[56:57], v[60:61] op_sel_hi:[1,0]
	ds_write_b128 v90, v[56:59] offset:1152
	s_waitcnt vmcnt(25)
	v_cndmask_b32_e64 v56, v105, 1.0, s[12:13]
	v_pk_mul_f32 v[54:55], v[54:55], v[56:57] op_sel_hi:[1,0]
	v_pk_mul_f32 v[52:53], v[52:53], v[56:57] op_sel_hi:[1,0]
	ds_write_b128 v90, v[52:55] offset:2304
	s_waitcnt vmcnt(24)
	v_cndmask_b32_e64 v52, v104, 1.0, s[12:13]
	v_pk_mul_f32 v[50:51], v[50:51], v[52:53] op_sel_hi:[1,0]
	v_pk_mul_f32 v[48:49], v[48:49], v[52:53] op_sel_hi:[1,0]
	ds_write_b128 v90, v[48:51] offset:3456
	s_waitcnt vmcnt(23)
	v_cndmask_b32_e64 v48, v103, 1.0, s[12:13]
	v_pk_mul_f32 v[46:47], v[46:47], v[48:49] op_sel_hi:[1,0]
	v_pk_mul_f32 v[44:45], v[44:45], v[48:49] op_sel_hi:[1,0]
	ds_write_b128 v90, v[44:47] offset:4608
	s_waitcnt vmcnt(22)
	v_cndmask_b32_e64 v44, v102, 1.0, s[12:13]
	v_pk_mul_f32 v[42:43], v[42:43], v[44:45] op_sel_hi:[1,0]
	v_pk_mul_f32 v[40:41], v[40:41], v[44:45] op_sel_hi:[1,0]
	ds_write_b128 v90, v[40:43] offset:5760
	s_waitcnt vmcnt(21)
	v_cndmask_b32_e64 v40, v101, 1.0, s[12:13]
	v_pk_mul_f32 v[38:39], v[38:39], v[40:41] op_sel_hi:[1,0]
	v_pk_mul_f32 v[36:37], v[36:37], v[40:41] op_sel_hi:[1,0]
	ds_write_b128 v90, v[36:39] offset:6912
	s_waitcnt vmcnt(20)
	v_cndmask_b32_e64 v36, v100, 1.0, s[12:13]
	v_pk_mul_f32 v[34:35], v[34:35], v[36:37] op_sel_hi:[1,0]
	v_pk_mul_f32 v[32:33], v[32:33], v[36:37] op_sel_hi:[1,0]
	ds_write_b128 v90, v[32:35] offset:8064
	s_waitcnt lgkmcnt(0)
	ds_read2_b32 v[32:33], v91 offset1:36
	ds_read2_b32 v[34:35], v91 offset0:72 offset1:108
	ds_read2_b32 v[36:37], v91 offset0:144 offset1:180
	ds_read2_b32 v[38:39], v91 offset0:216 offset1:252
	v_readlane_b32 s10, v253, 54
	s_waitcnt lgkmcnt(3)
	v_cvt_pk_bf16_f32 v32, v32, v33
	s_waitcnt lgkmcnt(2)
	v_cvt_pk_bf16_f32 v33, v34, v35
	s_waitcnt lgkmcnt(1)
	v_cvt_pk_bf16_f32 v34, v36, v37
	s_waitcnt lgkmcnt(0)
	v_cvt_pk_bf16_f32 v35, v38, v39
	ds_read2_b32 v[36:37], v108 offset0:64 offset1:100
	ds_read2_b32 v[38:39], v108 offset0:136 offset1:172
	ds_read2_b32 v[40:41], v108 offset0:208 offset1:244
	ds_read2_b32 v[42:43], v110 offset0:24 offset1:60
	global_store_dwordx4 v[72:73], v[32:35], off
	s_add_i32 s18, s18, s10
	s_add_i32 s10, s63, s18
	s_waitcnt lgkmcnt(3)
	v_cvt_pk_bf16_f32 v32, v36, v37
	s_waitcnt lgkmcnt(2)
	v_cvt_pk_bf16_f32 v33, v38, v39
	s_waitcnt lgkmcnt(1)
	v_cvt_pk_bf16_f32 v34, v40, v41
	s_waitcnt lgkmcnt(0)
	v_cvt_pk_bf16_f32 v35, v42, v43
	ds_read2_b32 v[36:37], v109 offset0:128 offset1:164
	ds_read2_b32 v[38:39], v109 offset0:200 offset1:236
	ds_read2_b32 v[40:41], v111 offset0:16 offset1:52
	ds_read2_b32 v[42:43], v111 offset0:88 offset1:124
	global_store_dwordx4 v[72:73], v[32:35], off offset:32
	s_cmpk_gt_i32 s10, 0x2fff
	s_cselect_b64 s[12:13], -1, 0
	s_waitcnt lgkmcnt(3)
	v_cvt_pk_bf16_f32 v32, v36, v37
	s_waitcnt lgkmcnt(2)
	v_cvt_pk_bf16_f32 v33, v38, v39
	s_waitcnt lgkmcnt(1)
	v_cvt_pk_bf16_f32 v34, v40, v41
	s_waitcnt lgkmcnt(0)
	v_cvt_pk_bf16_f32 v35, v42, v43
	ds_read2_b32 v[36:37], v113 offset0:192 offset1:228
	ds_read2_b32 v[38:39], v112 offset0:8 offset1:44
	ds_read2_b32 v[40:41], v112 offset0:80 offset1:116
	ds_read2_b32 v[42:43], v112 offset0:152 offset1:188
	global_store_dwordx4 v[72:73], v[32:35], off offset:64
	s_mov_b32 s19, s11
	s_mov_b32 s10, s14
	s_waitcnt lgkmcnt(3)
	v_cvt_pk_bf16_f32 v32, v36, v37
	s_waitcnt lgkmcnt(2)
	v_cvt_pk_bf16_f32 v33, v38, v39
	s_waitcnt lgkmcnt(1)
	v_cvt_pk_bf16_f32 v34, v40, v41
	s_waitcnt lgkmcnt(0)
	v_cvt_pk_bf16_f32 v35, v42, v43
	global_store_dwordx4 v[72:73], v[32:35], off offset:96
	s_waitcnt lgkmcnt(0)
	v_mov_b64_e32 v[80:81], v[86:87]
	v_mov_b64_e32 v[78:79], v[84:85]
	v_mov_b64_e32 v[76:77], v[82:83]

; #define LAS __attribute__((address_space(3)))
; DI unsigned pk2(float a, float b) { f32x2 v = {a, b}; hbf16x2 r = __builtin_convertvector(v, hbf16x2); return __builtin_bit_cast(unsigned, r); }
; template <int NS>
; DI void ti_decode(TItem& ti, int it, const CStack (&st)[NS], int lane) {
;     int base = 0;
; #pragma unroll
;     for (int j = 0; j < NS; ++j) {
;         const int nblk = st[j].N / 32, per = (st[j].K / 64) * nblk, tot = st[j].L * per;
;         if (it >= base && (it < base + tot || j == NS - 1)) {
;             const int K = st[j].K, N = st[j].N, r0 = it - base, l = r0 / per, rem = r0 - l * per, kb = rem / nblk, nb = rem - kb * nblk, k0 = 64 * kb;
;             ti.src = st[j].W + (size_t)l * K * N + (size_t)(k0 + (lane >> 3)) * N + (st[j].perm ? even_src32(nb) : 32 * nb) + 4 * (lane & 7);
;             ti.dst = st[j].WT + (size_t)l * K * N + (size_t)(32 * nb + (lane & 31)) * K + k0 + 8 * (lane >> 5);
;             ti.hasg = st[j].gk != nullptr; ti.gp = ti.hasg ? st[j].gk + (size_t)l * st[j].gstride + k0 + (lane >> 3) : ti.src;
;             ti.N = N;
;         }
;         base += tot;
;     }
; }
; #pragma unroll
;     for (int j = 0; j < NS; ++j) t += st[j].L * (st[j].K / 64) * (st[j].N / 32);
;     return t; }
; DI void ti_load(f32x4 (&v)[8], float (&g)[8], const TItem& ti) {
; #pragma unroll
;     for (int i = 0; i < 8; ++i) v[i] = *(const f32x4*)(ti.src + (size_t)(8 * i) * ti.N);
; #pragma unroll
;     for (int i = 0; i < 8; ++i) g[i] = ti.gp[8 * i];
; }
; DI void ti_finish(const f32x4 (&v)[8], const float (&g)[8], const TItem& ti, LAS float* scr, int lane) {
;     const int q8 = lane & 7, kr = lane >> 3;
; #pragma unroll
;     for (int i = 0; i < 8; ++i) *(LAS f32x4*)(scr + (8 * i + kr) * 36 + 4 * q8) = v[i] * (ti.hasg ? g[i] : 1.0f);
;     asm volatile("s_waitcnt lgkmcnt(0)" ::: "memory");
;     const int n = lane & 31, kc = lane >> 5;
; #pragma unroll
;     for (int p2 = 0; p2 < 4; ++p2) { const int c = 2 * p2 + kc; const LAS float* s = scr + (8 * c) * 36 + n;
;         u32x4 o; o.x = pk2(s[0], s[36]); o.y = pk2(s[72], s[108]); o.z = pk2(s[144], s[180]); o.w = pk2(s[216], s[252]);
;         *(u32x4*)(ti.dst + 16 * p2) = o; }
;     asm volatile("s_waitcnt lgkmcnt(0)" ::: "memory");
; }
.LBB0_700:
	s_lshl_b64 s[14:15], s[14:15], 5
	v_lshl_add_u64 v[32:33], v[70:71], 0, s[14:15]
	v_lshl_add_u64 v[34:35], v[32:33], 0, s[14:15]
	global_load_dwordx4 v[56:59], v[32:33], off nt
	global_load_dwordx4 v[52:55], v[34:35], off nt
	v_lshl_add_u64 v[32:33], v[34:35], 0, s[14:15]
	v_lshl_add_u64 v[34:35], v[32:33], 0, s[14:15]
	global_load_dwordx4 v[48:51], v[32:33], off nt
	global_load_dwordx4 v[44:47], v[34:35], off nt
	v_lshl_add_u64 v[32:33], v[34:35], 0, s[14:15]
	v_lshl_add_u64 v[34:35], v[32:33], 0, s[14:15]
	global_load_dwordx4 v[40:43], v[32:33], off nt
	global_load_dwordx4 v[36:39], v[34:35], off nt
	v_lshl_add_u64 v[32:33], v[34:35], 0, s[14:15]
	global_load_dwordx4 v[60:63], v[70:71], off nt
	s_nop 0
	global_load_dwordx4 v[32:35], v[32:33], off nt
	s_nop 0
	global_load_dword v107, v[74:75], off
	global_load_dword v106, v[74:75], off offset:32
	global_load_dword v105, v[74:75], off offset:64
	global_load_dword v104, v[74:75], off offset:96
	global_load_dword v103, v[74:75], off offset:128
	global_load_dword v102, v[74:75], off offset:160
	global_load_dword v101, v[74:75], off offset:192
	global_load_dword v100, v[74:75], off offset:224
	s_cmp_eq_u32 s19, 0
	s_cselect_b64 s[14:15], -1, 0
	s_waitcnt vmcnt(23)
	v_cndmask_b32_e64 v82, v99, 1.0, s[14:15]
	v_pk_mul_f32 v[30:31], v[30:31], v[82:83] op_sel_hi:[1,0]
	v_pk_mul_f32 v[28:29], v[28:29], v[82:83] op_sel_hi:[1,0]
	ds_write_b128 v90, v[28:31]
	s_waitcnt vmcnt(22)
	v_cndmask_b32_e64 v28, v98, 1.0, s[14:15]
	v_pk_mul_f32 v[26:27], v[26:27], v[28:29] op_sel_hi:[1,0]
	v_pk_mul_f32 v[24:25], v[24:25], v[28:29] op_sel_hi:[1,0]
	ds_write_b128 v90, v[24:27] offset:1152
	s_waitcnt vmcnt(21)
	v_cndmask_b32_e64 v24, v97, 1.0, s[14:15]
	v_pk_mul_f32 v[22:23], v[22:23], v[24:25] op_sel_hi:[1,0]
	v_pk_mul_f32 v[20:21], v[20:21], v[24:25] op_sel_hi:[1,0]
	ds_write_b128 v90, v[20:23] offset:2304
	s_waitcnt vmcnt(20)
	v_cndmask_b32_e64 v20, v96, 1.0, s[14:15]
	v_pk_mul_f32 v[18:19], v[18:19], v[20:21] op_sel_hi:[1,0]
	v_pk_mul_f32 v[16:17], v[16:17], v[20:21] op_sel_hi:[1,0]
	ds_write_b128 v90, v[16:19] offset:3456
	s_waitcnt vmcnt(19)
	v_cndmask_b32_e64 v16, v95, 1.0, s[14:15]
	v_pk_mul_f32 v[14:15], v[14:15], v[16:17] op_sel_hi:[1,0]
	v_pk_mul_f32 v[12:13], v[12:13], v[16:17] op_sel_hi:[1,0]
	ds_write_b128 v90, v[12:15] offset:4608
	s_waitcnt vmcnt(18)
	v_cndmask_b32_e64 v12, v94, 1.0, s[14:15]
	v_pk_mul_f32 v[6:7], v[6:7], v[12:13] op_sel_hi:[1,0]
	v_pk_mul_f32 v[4:5], v[4:5], v[12:13] op_sel_hi:[1,0]
	ds_write_b128 v90, v[4:7] offset:5760
	s_waitcnt vmcnt(17)
	v_cndmask_b32_e64 v4, v93, 1.0, s[14:15]
	v_pk_mul_f32 v[2:3], v[2:3], v[4:5] op_sel_hi:[1,0]
	v_pk_mul_f32 v[0:1], v[0:1], v[4:5] op_sel_hi:[1,0]
	ds_write_b128 v90, v[0:3] offset:6912
	s_waitcnt vmcnt(16)
	v_cndmask_b32_e64 v0, v92, 1.0, s[14:15]
	v_pk_mul_f32 v[2:3], v[10:11], v[0:1] op_sel_hi:[1,0]
	v_pk_mul_f32 v[0:1], v[8:9], v[0:1] op_sel_hi:[1,0]
	ds_write_b128 v90, v[0:3] offset:8064
	s_waitcnt lgkmcnt(0)
	ds_read2_b32 v[0:1], v91 offset1:36
	ds_read2_b32 v[2:3], v91 offset0:72 offset1:108
	ds_read2_b32 v[4:5], v91 offset0:144 offset1:180
	ds_read2_b32 v[6:7], v91 offset0:216 offset1:252
	v_add_u32_e32 v108, 0x800, v91
	v_add_u32_e32 v110, 0xc00, v91
	s_waitcnt lgkmcnt(3)
	v_cvt_pk_bf16_f32 v0, v0, v1
	s_waitcnt lgkmcnt(2)
	v_cvt_pk_bf16_f32 v1, v2, v3
	s_waitcnt lgkmcnt(1)
	v_cvt_pk_bf16_f32 v2, v4, v5
	s_waitcnt lgkmcnt(0)
	v_cvt_pk_bf16_f32 v3, v6, v7
	ds_read2_b32 v[4:5], v108 offset0:64 offset1:100
	ds_read2_b32 v[6:7], v108 offset0:136 offset1:172
	ds_read2_b32 v[8:9], v108 offset0:208 offset1:244
	ds_read2_b32 v[10:11], v110 offset0:24 offset1:60
	global_store_dwordx4 v[78:79], v[0:3], off
	v_add_u32_e32 v109, 0x1000, v91
	v_add_u32_e32 v111, 0x1400, v91
	s_waitcnt lgkmcnt(3)
	v_cvt_pk_bf16_f32 v0, v4, v5
	s_waitcnt lgkmcnt(2)
	v_cvt_pk_bf16_f32 v1, v6, v7
	s_waitcnt lgkmcnt(1)
	v_cvt_pk_bf16_f32 v2, v8, v9
	s_waitcnt lgkmcnt(0)
	v_cvt_pk_bf16_f32 v3, v10, v11
	ds_read2_b32 v[4:5], v109 offset0:128 offset1:164
	ds_read2_b32 v[6:7], v109 offset0:200 offset1:236
	ds_read2_b32 v[8:9], v111 offset0:16 offset1:52
	ds_read2_b32 v[10:11], v111 offset0:88 offset1:124
	global_store_dwordx4 v[78:79], v[0:3], off offset:32
	v_add_u32_e32 v113, 0x1800, v91
	v_add_u32_e32 v112, 0x1c00, v91
	s_waitcnt lgkmcnt(3)
	v_cvt_pk_bf16_f32 v0, v4, v5
	s_waitcnt lgkmcnt(2)
	v_cvt_pk_bf16_f32 v1, v6, v7
	s_waitcnt lgkmcnt(1)
	v_cvt_pk_bf16_f32 v2, v8, v9
	s_waitcnt lgkmcnt(0)
	v_cvt_pk_bf16_f32 v3, v10, v11
	ds_read2_b32 v[4:5], v113 offset0:192 offset1:228
	ds_read2_b32 v[6:7], v112 offset0:8 offset1:44
	ds_read2_b32 v[8:9], v112 offset0:80 offset1:116
	ds_read2_b32 v[10:11], v112 offset0:152 offset1:188
	global_store_dwordx4 v[78:79], v[0:3], off offset:64
	s_andn2_b64 vcc, exec, s[12:13]
	s_mov_b64 s[12:13], -1
	s_waitcnt lgkmcnt(3)
	v_cvt_pk_bf16_f32 v0, v4, v5
	s_waitcnt lgkmcnt(2)
	v_cvt_pk_bf16_f32 v1, v6, v7
	s_waitcnt lgkmcnt(1)
	v_cvt_pk_bf16_f32 v2, v8, v9
	s_waitcnt lgkmcnt(0)
	v_cvt_pk_bf16_f32 v3, v10, v11
	global_store_dwordx4 v[78:79], v[0:3], off offset:96
	s_waitcnt lgkmcnt(0)
	s_cbranch_vccnz .LBB0_692
	v_readlane_b32 s12, v253, 55
	s_add_i32 s12, s12, s18
	s_cmpk_lt_i32 s12, 0x3000
	s_cselect_b32 s11, s12, s11
	s_cmpk_gt_u32 s11, 0x1fff
	s_cbranch_scc1 .LBB0_703
	s_and_b32 s10, s11, 0x1fc0
	v_or_b32_e32 v0, s10, v88
	s_lshl_b32 s12, s11, 5
	v_lshlrev_b32_e32 v152, 13, v0
	s_and_b32 s12, s12, 0x7e0
	v_lshl_add_u64 v[0:1], s[0:1], 0, v[152:153]
	s_lshl_b32 s72, s12, 2
	v_lshl_add_u64 v[0:1], v[0:1], 0, s[72:73]
	v_mov_b32_e32 v65, v153
	v_lshl_add_u64 v[76:77], v[0:1], 0, v[64:65]
	v_or_b32_e32 v0, s12, v89
	v_lshlrev_b32_e32 v152, 14, v0
	v_lshl_add_u64 v[0:1], s[2:3], 0, v[152:153]
	s_lshl_b32 s72, s10, 1
	v_lshl_add_u64 v[0:1], v[0:1], 0, s[72:73]
	v_mov_b32_e32 v67, v153
	v_lshl_add_u64 v[78:79], v[0:1], 0, v[66:67]
	s_mov_b32 s19, 0
	s_movk_i32 s10, 0x800
	v_mov_b64_e32 v[80:81], v[76:77]
